# v27: v26 + P5 state-load waits moved in front of the sub-chunk loop (prefetch overlaps the whole sub-chunk)
# baseline (speedup 1.0000x reference)
; template <bool OUT> DI void hgrn_item(LAS unsigned char* lds, bf16_t* proj, float* hst, float* hdv, const float* normw, int item, bool dry) {
;     ...
;     float* hs = hst + (size_t)item * 16384 + (size_t)(w * 8) * 256 + lane * 4;
;     if (OUT) {
; #pragma unroll
;         for (int i = 0; i < 8; ++i) st[i] = *(const f32x4*)(hs + i * 256);
;     } else {
; #pragma unroll
;         for (int i = 0; i < 8; ++i) st[i] = (f32x4){0.f, 0.f, 0.f, 0.f};
;     }
;     float btot = 0.f;
;     unsigned rg[8], rqv[8], rvv[8];
;     ...
;     HG_LOAD(0);
.LBB0_1169:
	s_lshl_b32 s14, s83, 1
	v_readfirstlane_b32 s21, v183
	s_ashr_i32 s17, s16, 31
	s_bfe_u32 s22, s40, 0x40008
	s_and_b32 s14, s14, 0x300
	s_and_b32 s85, s40, 0xf00
	s_lshr_b32 s20, s21, 6
	s_lshl_b64 s[18:19], s[16:17], 16
	s_add_u32 s17, s70, s18
	s_addc_u32 s23, s71, s19
	s_lshl_b32 s18, s20, 3
	s_mov_b32 s19, s15
	s_lshl_b64 s[18:19], s[18:19], 10
	s_add_u32 s18, s17, s18
	s_addc_u32 s19, s23, s19
	s_ashr_i32 s36, s16, 6
	s_ashr_i32 s37, s36, 31
	s_lshl_b32 s17, s16, 8
	s_lshl_b64 s[34:35], s[36:37], 12
	s_and_b32 s17, s17, 0xf00
	s_or_b32 s17, s34, s17
	v_or_b32_e32 v2, s17, v76
	v_mad_u64_u32 v[2:3], s[24:25], v2, s50, v[90:91]
	s_lshl_b32 s17, s16, 4
	v_mad_i32_i24 v3, s35, v114, v3
	s_and_b32 s24, s17, 0x300
	s_mov_b32 s25, s15
	v_lshl_add_u64 v[2:3], v[2:3], 0, s[24:25]
	v_lshl_add_u64 v[2:3], v[2:3], 0, v[88:89]
	v_add_co_u32_e32 v4, vcc, s51, v2
	v_lshl_add_u64 v[14:15], s[18:19], 0, v[74:75]
	s_nop 0
	v_addc_co_u32_e32 v5, vcc, 0, v3, vcc
	v_add_co_u32_e32 v6, vcc, s52, v2
	s_bfe_u32 s17, s21, 0x20006
	s_nop 0
	v_addc_co_u32_e32 v7, vcc, 0, v3, vcc
	v_add_co_u32_e32 v8, vcc, s53, v2
	s_and_b32 s86, s21, 0xffffffc0
	s_nop 0
	v_addc_co_u32_e32 v9, vcc, 0, v3, vcc
	global_load_ushort v184, v[2:3], off offset:2560
	global_load_ushort v185, v[4:5], off offset:3072
	global_load_ushort v186, v[2:3], off offset:3584
	global_load_ushort v187, v[6:7], off
	global_load_ushort v188, v[8:9], off offset:3584
	global_load_ushort v189, v[8:9], off offset:2560
	global_load_ushort v190, v[4:5], off offset:2048
	global_load_ushort v191, v[2:3], off offset:1536
	v_add_co_u32_e32 v4, vcc, s54, v2
	s_lshr_b32 s21, s21, 8
	s_nop 0
	v_addc_co_u32_e32 v5, vcc, 0, v3, vcc
	v_add_co_u32_e32 v6, vcc, s55, v2
	s_cmp_le_u32 s17, s21
	s_nop 0
	v_addc_co_u32_e32 v7, vcc, 0, v3, vcc
	v_add_co_u32_e32 v8, vcc, s58, v2
	s_mul_i32 s37, s22, 0x320000
	s_nop 0
	v_addc_co_u32_e32 v9, vcc, 0, v3, vcc
	v_add_co_u32_e32 v10, vcc, s59, v2
	v_lshl_or_b32 v120, s17, 4, v1
	s_nop 0
	v_addc_co_u32_e32 v11, vcc, 0, v3, vcc
	v_add_co_u32_e32 v12, vcc, s66, v2
	s_mul_hi_i32 s87, s36, 0x3200000
	s_nop 0
	v_addc_co_u32_e32 v13, vcc, 0, v3, vcc
	global_load_ushort v192, v[4:5], off
	global_load_ushort v193, v[6:7], off offset:512
	global_load_ushort v194, v[8:9], off offset:3072
	global_load_ushort v195, v[10:11], off offset:512
	global_load_ushort v196, v[12:13], off offset:1024
	global_load_ushort v197, v[10:11], off offset:1536
	global_load_ushort v198, v[12:13], off
	global_load_ushort v199, v[4:5], off offset:1024
	v_add_co_u32_e32 v4, vcc, s67, v2
	s_mul_i32 s36, s36, 0x3200000
	s_nop 0
	v_addc_co_u32_e32 v5, vcc, 0, v3, vcc
	v_add_co_u32_e32 v6, vcc, s68, v2
	v_add_u32_e32 v125, s86, v109
	s_nop 0
	v_addc_co_u32_e32 v7, vcc, 0, v3, vcc
	v_add_co_u32_e32 v8, vcc, s69, v2
	v_addc_co_u32_e32 v9, vcc, 0, v3, vcc
	global_load_ushort v200, v[12:13], off offset:2048
	global_load_ushort v201, v[4:5], off offset:3584
	global_load_ushort v202, v[6:7], off offset:1536
	global_load_ushort v203, v[8:9], off offset:2048
	global_load_ushort v204, v[6:7], off offset:2560
	global_load_ushort v205, v[8:9], off offset:3072
	global_load_ushort v206, v[8:9], off offset:1024
	global_load_ushort v207, v[6:7], off offset:512
	v_add_co_u32_e32 v4, vcc, s72, v2
	s_nop 0
	v_addc_co_u32_e32 v5, vcc, 0, v3, vcc
	v_add_co_u32_e32 v6, vcc, s73, v2
	s_nop 0
	v_addc_co_u32_e32 v7, vcc, 0, v3, vcc
	v_add_co_u32_e32 v8, vcc, s74, v2
	s_nop 0
	v_addc_co_u32_e32 v9, vcc, 0, v3, vcc
	v_add_co_u32_e32 v10, vcc, s75, v2
	s_nop 0
	v_addc_co_u32_e32 v11, vcc, 0, v3, vcc
	global_load_ushort v208, v[4:5], off offset:2560
	global_load_ushort v209, v[6:7], off offset:3072
	global_load_ushort v210, v[4:5], off offset:3584
	global_load_ushort v211, v[8:9], off
	global_load_ushort v212, v[10:11], off offset:3584
	global_load_ushort v213, v[10:11], off offset:2560
	global_load_ushort v214, v[6:7], off offset:2048
	global_load_ushort v215, v[4:5], off offset:1536
	v_add_co_u32_e32 v4, vcc, s76, v2
	s_nop 0
	v_addc_co_u32_e32 v5, vcc, 0, v3, vcc
	v_add_co_u32_e32 v6, vcc, s77, v2
	s_nop 0
	v_addc_co_u32_e32 v7, vcc, 0, v3, vcc
	v_add_co_u32_e32 v8, vcc, s78, v2
	s_nop 0
	v_addc_co_u32_e32 v9, vcc, 0, v3, vcc
	v_add_co_u32_e32 v10, vcc, s79, v2
	s_nop 0
	v_addc_co_u32_e32 v11, vcc, 0, v3, vcc
	v_add_co_u32_e32 v12, vcc, s80, v2
	s_nop 0
	v_addc_co_u32_e32 v13, vcc, 0, v3, vcc
	global_load_ushort v216, v[4:5], off
	global_load_ushort v217, v[6:7], off offset:512
	global_load_ushort v218, v[8:9], off offset:3072
	global_load_ushort v219, v[10:11], off offset:512
	global_load_ushort v220, v[12:13], off offset:1024
	global_load_ushort v221, v[10:11], off offset:1536
	global_load_ushort v222, v[12:13], off
	global_load_ushort v223, v[4:5], off offset:1024
	v_add_co_u32_e32 v4, vcc, s81, v2
	s_nop 0
	v_addc_co_u32_e32 v5, vcc, 0, v3, vcc
	v_add_co_u32_e32 v6, vcc, s82, v2
	s_nop 0
	v_addc_co_u32_e32 v7, vcc, 0, v3, vcc
	v_add_co_u32_e32 v2, vcc, s84, v2
	v_addc_co_u32_e32 v3, vcc, 0, v3, vcc
	v_add_co_u32_e32 v30, vcc, s47, v14
	global_load_ushort v224, v[12:13], off offset:2048
	global_load_ushort v225, v[4:5], off offset:3584
	global_load_ushort v226, v[6:7], off offset:1536
	global_load_ushort v227, v[2:3], off offset:2048
	global_load_ushort v228, v[6:7], off offset:2560
	global_load_ushort v229, v[2:3], off offset:3072
	global_load_ushort v230, v[2:3], off offset:1024
	global_load_ushort v231, v[6:7], off offset:512
	v_addc_co_u32_e32 v31, vcc, 0, v15, vcc
	global_load_dwordx4 v[6:9], v74, s[18:19]
	global_load_dwordx4 v[10:13], v74, s[18:19] offset:1024
	global_load_dwordx4 v[2:5], v74, s[18:19] offset:2048
; #define LAS __attribute__((address_space(3)))
; DI unsigned pk2(float lo, float hi) { f32x2 v = {lo, hi}; bfv2 b = __builtin_convertvector(v, bfv2); return __builtin_bit_cast(unsigned, b); }
; DI bf16_t f2bf(float x) { return (bf16_t)(pk2(x, 0.f) & 0xffffu); }
; DI float bflo(unsigned w) { return __uint_as_float(w << 16); }
; DI float bfhi(unsigned w) { return __uint_as_float(w & 0xffff0000u); }
; #define MFMA16(a, b, c) __builtin_amdgcn_mfma_f32_16x16x32_bf16((a), (b), (c), 0, 0, 0)
; template <bool OUT> DI void hgrn_item(LAS unsigned char* lds, bf16_t* proj, float* hst, float* hdv, const float* normw, int item, bool dry) {
;     ...
;     HG_LOAD(0);
; #pragma unroll 1
;     for (int sc = 0; sc < 4; ++sc) {
;         const size_t row0 = (size_t)b * 4096 + c * 256 + sc * 64;
;         float gl[16], qv[16];
; #pragma unroll
;         for (int i = 0; i < 8; ++i) { gl[2 * i] = bflo(rg[i]); gl[2 * i + 1] = bfhi(rg[i]); if (OUT) { qv[2 * i] = bflo(rqv[i]); qv[2 * i + 1] = bfhi(rqv[i]); } }
;         *(LAS u32x4*)(VT + d * TP + tq * 16) = (u32x4){rvv[0], rvv[1], rvv[2], rvv[3]};
;         *(LAS u32x4*)(VT + d * TP + tq * 16 + 8) = (u32x4){rvv[4], rvv[5], rvv[6], rvv[7]};
;     ...
;                 for (int r = 0; r < 4; ++r) { const int tt = 16 * ti + 4 * rq + r, ss = 16 * sj + e16; Ab[tt * TP + ss] = (sj <= ti && ss <= tt) ? f2bf(a[r]) : (bf16_t)0; }
;             }
; #pragma unroll
;             for (int ti = 0; ti < 4; ++ti) { o[ti] = (f32x4){0.f, 0.f, 0.f, 0.f};
; #pragma unroll
;                 for (int ks = 0; ks < 4; ++ks) { const LAS bf16_t* qp = Qt + (16 * ti + e16) * QP + 32 * ks + 4 * rq; const u32x2 q0 = *(const LAS u32x2*)qp, q1 = *(const LAS u32x2*)(qp + 16);
;                     u32x4 qa = {q0.x, q0.y, q1.x, q1.y};
;                     u32x4 sb; sb.x = pk2(st[2 * ks][0], st[2 * ks][1]); sb.y = pk2(st[2 * ks][2], st[2 * ks][3]); sb.z = pk2(st[2 * ks + 1][0], st[2 * ks + 1][1]); sb.w = pk2(st[2 * ks + 1][2], st[2 * ks + 1][3]);
;                     o[ti] = MFMA16(__builtin_bit_cast(bf16x8, qa), __builtin_bit_cast(bf16x8, sb), o[ti]); } }
	global_load_dwordx4 v[18:21], v74, s[18:19] offset:3072
	global_load_dwordx4 v[14:17], v[30:31], off
	global_load_dwordx4 v[26:29], v[30:31], off offset:1024
	global_load_dwordx4 v[22:25], v[30:31], off offset:2048
	s_nop 0
	global_load_dwordx4 v[30:33], v[30:31], off offset:3072
	s_cselect_b64 s[18:19], -1, 0
	s_cmp_gt_u32 s17, s21
	v_lshl_or_b32 v58, s20, 4, v1
	s_cselect_b64 s[30:31], -1, 0
	s_add_i32 s20, s20, 8
	s_lshl_b32 s24, s21, 4
	s_lshr_b32 s25, s20, 2
	s_cmp_gt_u32 s17, s25
	s_cselect_b64 s[20:21], -1, 0
	s_cmp_le_u32 s17, s25
	s_cselect_b64 s[22:23], -1, 0
	s_lshl_b32 s17, s25, 4
	v_mul_lo_u32 v62, v58, s39
	v_or_b32_e32 v58, s24, v1
	v_mul_u32_u24_e32 v63, 0x110, v120
	v_add_u32_e32 v121, v93, v62
	v_add_u32_e32 v126, v105, v63
	v_mul_lo_u32 v64, v58, s38
	v_or_b32_e32 v58, s17, v1
	v_mul_lo_u32 v65, v58, s38
	v_or_b32_e32 v58, s24, v104
	v_cmp_gt_u32_e32 vcc, v120, v58
	v_or_b32_e32 v59, 1, v58
	s_or_b64 s[24:25], s[30:31], vcc
	v_cmp_gt_u32_e32 vcc, v120, v59
	v_or_b32_e32 v59, 2, v58
	v_mul_lo_u32 v66, v58, s39
	s_or_b64 s[26:27], s[30:31], vcc
	v_cmp_gt_u32_e32 vcc, v120, v59
	v_or_b32_e32 v58, 3, v58
	s_or_b64 s[28:29], s[30:31], vcc
	v_cmp_gt_u32_e32 vcc, v120, v58
	s_or_b64 s[30:31], s[30:31], vcc
	s_add_u32 s36, s36, s37
	v_or_b32_e32 v58, s34, v82
	s_addc_u32 s37, s87, 0
	s_or_b32 s36, s36, s14
	v_or_b32_e32 v60, s85, v58
	v_mov_b64_e32 v[58:59], s[14:15]
	v_add_u32_e32 v122, v105, v64
	v_add_u32_e32 v124, v105, v65
	v_lshl_add_u64 v[94:95], v[84:85], 0, s[36:37]
	v_mad_u64_u32 v[60:61], s[36:37], v60, s50, v[58:59]
	v_mad_i32_i24 v61, s35, v114, v61
	v_lshl_add_u64 v[96:97], v[86:87], 0, v[60:61]
	v_or_b32_e32 v60, s34, v80
	v_or_b32_e32 v60, s85, v60
	v_mad_u64_u32 v[58:59], s[36:37], v60, s50, v[58:59]
	v_lshl_add_u32 v92, v120, 1, s33
	v_mad_i32_i24 v59, s35, v114, v59
	v_lshl_add_u64 v[98:99], v[86:87], 0, v[58:59]
	s_mov_b64 s[34:35], 0
	v_add_u32_e32 v123, v92, v66
	s_waitcnt vmcnt(54)
	v_lshl_or_b32 v42, v185, 16, v184
	s_waitcnt vmcnt(52)
	v_lshl_or_b32 v34, v187, 16, v186
	s_waitcnt vmcnt(48)
	v_lshl_or_b32 v46, v190, 16, v191
	v_mov_b32_e32 v127, v46
	v_mov_b32_e32 v129, v42
	s_waitcnt vmcnt(47)
	v_lshl_or_b32 v43, v192, 16, v188
	s_waitcnt vmcnt(40)
	v_lshl_or_b32 v35, v199, 16, v193
	v_lshl_or_b32 v44, v196, 16, v195
	v_lshl_or_b32 v47, v194, 16, v189
	v_mov_b32_e32 v128, v47
	v_mov_b32_e32 v131, v43
	v_mov_b32_e32 v133, v44
	s_waitcnt vmcnt(39)
	v_lshl_or_b32 v36, v200, 16, v197
	s_waitcnt vmcnt(38)
	v_lshl_or_b32 v49, v198, 16, v201
	s_waitcnt vmcnt(32)
	v_lshl_or_b32 v51, v206, 16, v207
	s_waitcnt vmcnt(28)
	v_lshl_or_b32 v38, v211, 16, v210
	v_lshl_or_b32 v45, v203, 16, v202
	s_waitcnt vmcnt(24)
	v_lshl_or_b32 v52, v214, 16, v215
	v_lshl_or_b32 v50, v209, 16, v208
	v_lshl_or_b32 v37, v205, 16, v204
	v_mov_b32_e32 v130, v49
	v_mov_b32_e32 v132, v51
	v_mov_b32_e32 v134, v52
	v_mov_b32_e32 v135, v45
	v_mov_b32_e32 v137, v50
	s_waitcnt vmcnt(23)
	v_lshl_or_b32 v55, v216, 16, v212
	s_waitcnt vmcnt(21)
	v_lshl_or_b32 v53, v218, 16, v213
	s_waitcnt vmcnt(16)
	v_lshl_or_b32 v39, v223, 16, v217
	v_lshl_or_b32 v56, v220, 16, v219
	v_mov_b32_e32 v136, v53
	v_mov_b32_e32 v139, v55
	v_mov_b32_e32 v141, v56
	s_waitcnt vmcnt(15)
	v_lshl_or_b32 v40, v224, 16, v221
	s_waitcnt vmcnt(14)
	v_lshl_or_b32 v54, v222, 16, v225
	s_waitcnt vmcnt(12)
	v_lshl_or_b32 v57, v227, 16, v226
	s_waitcnt vmcnt(0)
	v_lshl_or_b32 v48, v230, 16, v231
	v_lshl_or_b32 v41, v229, 16, v228
	v_mov_b32_e32 v138, v54
	v_mov_b32_e32 v140, v48
	v_mov_b32_e32 v142, v57
	s_branch .LBB0_1171
.LBB0_1170:
	v_or_b32_e32 v56, s14, v104
	v_cmp_gt_u32_e32 vcc, v120, v56
	s_or_b64 s[36:37], s[20:21], vcc
	s_nop 3
	v_cvt_pk_bf16_f32 v50, v50, s0
	v_cndmask_b32_e64 v50, v50, 0, s[36:37]
	v_mad_u64_u32 v[54:55], s[36:37], v56, s39, v[92:93]
	ds_write_b16 v54, v50
	v_or_b32_e32 v50, 1, v56
	v_cmp_gt_u32_e32 vcc, v120, v50
	s_or_b64 s[36:37], s[20:21], vcc
	v_cvt_pk_bf16_f32 v50, v51, s0
	v_cndmask_b32_e64 v50, v50, 0, s[36:37]
	ds_write_b16 v54, v50 offset:144
	v_or_b32_e32 v50, 2, v56
	v_cmp_gt_u32_e32 vcc, v120, v50
	s_or_b64 s[36:37], s[20:21], vcc
	v_cvt_pk_bf16_f32 v50, v52, s0
	v_cndmask_b32_e64 v50, v50, 0, s[36:37]
	ds_write_b16 v54, v50 offset:288
	v_or_b32_e32 v50, 3, v56
	v_cmp_gt_u32_e32 vcc, v120, v50
	s_or_b64 s[36:37], s[20:21], vcc
	v_cvt_pk_bf16_f32 v50, v53, s0
	v_cndmask_b32_e64 v50, v50, 0, s[36:37]
	ds_write_b16 v54, v50 offset:432
	ds_read2_b64 v[50:53], v115 offset1:4
	ds_read2_b64 v[54:57], v115 offset0:8 offset1:12
	v_cvt_pk_bf16_f32 v66, v6, v7
	v_cvt_pk_bf16_f32 v67, v8, v9
	v_cvt_pk_bf16_f32 v68, v10, v11
	v_cvt_pk_bf16_f32 v69, v12, v13
	v_cvt_pk_bf16_f32 v70, v2, v3
	v_cvt_pk_bf16_f32 v71, v4, v5
	s_waitcnt lgkmcnt(1)
	v_mfma_f32_16x16x32_bf16 v[50:53], v[50:53], v[66:69], 0
	v_cvt_pk_bf16_f32 v72, v18, v19
	v_cvt_pk_bf16_f32 v73, v20, v21
	v_cvt_pk_bf16_f32 v100, v14, v15
	v_cvt_pk_bf16_f32 v101, v16, v17
	s_waitcnt lgkmcnt(0)
	v_mfma_f32_16x16x32_bf16 v[50:53], v[54:57], v[70:73], v[50:53]
	ds_read2_b64 v[54:57], v115 offset0:16 offset1:20
	v_cvt_pk_bf16_f32 v102, v26, v27
	v_cvt_pk_bf16_f32 v103, v28, v29
	v_cvt_pk_bf16_f32 v144, v22, v23
	v_cvt_pk_bf16_f32 v145, v24, v25
	s_waitcnt lgkmcnt(0)
	v_mfma_f32_16x16x32_bf16 v[50:53], v[54:57], v[100:103], v[50:53]
	ds_read2_b64 v[54:57], v115 offset0:24 offset1:28
	v_cvt_pk_bf16_f32 v146, v30, v31
	v_cvt_pk_bf16_f32 v147, v32, v33
	v_add_u32_e32 v62, 0x1000, v115
	ds_read2_b64 v[58:61], v62 offset0:40 offset1:44
	s_waitcnt lgkmcnt(1)
	v_mfma_f32_16x16x32_bf16 v[54:57], v[54:57], v[144:147], v[50:53]
	s_nop 2
	ds_read2_b64 v[50:53], v62 offset0:32 offset1:36
	v_add_u32_e32 v143, 0x2000, v115
	s_waitcnt lgkmcnt(0)
; #define LAS __attribute__((address_space(3)))
; DI unsigned pk2(float lo, float hi) { f32x2 v = {lo, hi}; bfv2 b = __builtin_convertvector(v, bfv2); return __builtin_bit_cast(unsigned, b); }
; #define MFMA16(a, b, c) __builtin_amdgcn_mfma_f32_16x16x32_bf16((a), (b), (c), 0, 0, 0)
; template <bool OUT> DI void hgrn_item(LAS unsigned char* lds, bf16_t* proj, float* hst, float* hdv, const float* normw, int item, bool dry) {
;     ...
;             for (int ti = 0; ti < 4; ++ti) { o[ti] = (f32x4){0.f, 0.f, 0.f, 0.f};
; #pragma unroll
;                 for (int ks = 0; ks < 4; ++ks) { const LAS bf16_t* qp = Qt + (16 * ti + e16) * QP + 32 * ks + 4 * rq; const u32x2 q0 = *(const LAS u32x2*)qp, q1 = *(const LAS u32x2*)(qp + 16);
;                     u32x4 qa = {q0.x, q0.y, q1.x, q1.y};
;                     u32x4 sb; sb.x = pk2(st[2 * ks][0], st[2 * ks][1]); sb.y = pk2(st[2 * ks][2], st[2 * ks][3]); sb.z = pk2(st[2 * ks + 1][0], st[2 * ks + 1][1]); sb.w = pk2(st[2 * ks + 1][2], st[2 * ks + 1][3]);
;                     o[ti] = MFMA16(__builtin_bit_cast(bf16x8, qa), __builtin_bit_cast(bf16x8, sb), o[ti]); } }
;         }
; #pragma unroll
;         for (int dt = 0; dt < 8; ++dt) {
; #pragma unroll
;             for (int ks = 0; ks < 2; ++ks) { const bf16x8 ka = *(const LAS bf16x8*)(KtT + (16 * dt + e16) * TP + 32 * ks + 8 * rq); st[dt] = MFMA16(ka, vfr[ks], st[dt]); }
;             const f32x4 dv = *(const LAS f32x4*)(Dv + 16 * dt + 4 * rq);
;             st[dt] *= dv;
;         }
	v_mfma_f32_16x16x32_bf16 v[50:53], v[50:53], v[66:69], 0
	v_mfma_f32_16x16x32_bf16 v[50:53], v[58:61], v[70:73], v[50:53]
	ds_read2_b64 v[58:61], v62 offset0:48 offset1:52
	s_waitcnt lgkmcnt(0)
	v_mfma_f32_16x16x32_bf16 v[50:53], v[58:61], v[100:103], v[50:53]
	ds_read2_b64 v[58:61], v62 offset0:56 offset1:60
	ds_read2_b64 v[62:65], v143 offset0:72 offset1:76
	s_waitcnt lgkmcnt(1)
	v_mfma_f32_16x16x32_bf16 v[58:61], v[58:61], v[144:147], v[50:53]
	s_nop 3
	ds_read2_b64 v[50:53], v143 offset0:64 offset1:68
	s_waitcnt lgkmcnt(0)
	v_mfma_f32_16x16x32_bf16 v[50:53], v[50:53], v[66:69], 0
	v_mfma_f32_16x16x32_bf16 v[50:53], v[62:65], v[70:73], v[50:53]
	ds_read2_b64 v[62:65], v143 offset0:80 offset1:84
	s_waitcnt lgkmcnt(0)
	v_mfma_f32_16x16x32_bf16 v[50:53], v[62:65], v[100:103], v[50:53]
	ds_read2_b64 v[62:65], v143 offset0:88 offset1:92
	v_add_u32_e32 v143, 0x3000, v115
	s_waitcnt lgkmcnt(0)
	v_mfma_f32_16x16x32_bf16 v[62:65], v[62:65], v[144:147], v[50:53]
	s_nop 3
	ds_read2_b64 v[50:53], v143 offset0:96 offset1:100
	s_waitcnt lgkmcnt(0)
	v_mfma_f32_16x16x32_bf16 v[50:53], v[50:53], v[66:69], 0
	ds_read2_b64 v[66:69], v143 offset0:104 offset1:108
	s_waitcnt lgkmcnt(0)
	v_mfma_f32_16x16x32_bf16 v[50:53], v[66:69], v[70:73], v[50:53]
	ds_read2_b64 v[66:69], v143 offset0:112 offset1:116
	s_waitcnt lgkmcnt(0)
	v_mfma_f32_16x16x32_bf16 v[50:53], v[66:69], v[100:103], v[50:53]
	ds_read2_b64 v[66:69], v143 offset0:120 offset1:124
	v_lshl_add_u64 v[102:103], v[98:99], 0, s[34:35]
	v_lshl_add_u64 v[100:101], v[96:97], 0, s[34:35]
	s_waitcnt lgkmcnt(0)
	v_mfma_f32_16x16x32_bf16 v[70:73], v[66:69], v[144:147], v[50:53]
	v_add_u32_e32 v66, v93, v108
	s_nop 1
	ds_read_b128 v[50:53], v66 offset:34816
	v_add_u32_e32 v67, 0x13c00, v93
	s_waitcnt lgkmcnt(0)
	v_mfma_f32_16x16x32_bf16 v[6:9], v[50:53], v[46:49], v[6:9]
	ds_read_b128 v[50:53], v66 offset:34880
	s_add_u32 s34, s34, 0xc8000
	s_addc_u32 s35, s35, 0
	s_waitcnt lgkmcnt(0)
	v_mfma_f32_16x16x32_bf16 v[6:9], v[50:53], v[42:45], v[6:9]
	ds_read_b128 v[50:53], v67
	s_cmp_lg_u32 s34, 0x320000
	s_waitcnt lgkmcnt(0)
	s_nop 4
	v_pk_mul_f32 v[8:9], v[8:9], v[52:53]
	v_pk_mul_f32 v[6:7], v[6:7], v[50:51]
	ds_read_b128 v[50:53], v66 offset:37120
	s_waitcnt lgkmcnt(0)
	v_mfma_f32_16x16x32_bf16 v[10:13], v[50:53], v[46:49], v[10:13]
	ds_read_b128 v[50:53], v66 offset:37184
	s_waitcnt lgkmcnt(0)
	v_mfma_f32_16x16x32_bf16 v[10:13], v[50:53], v[42:45], v[10:13]
	ds_read_b128 v[50:53], v67 offset:64
	s_waitcnt lgkmcnt(0)
	s_nop 5
	v_pk_mul_f32 v[12:13], v[12:13], v[52:53]
	v_pk_mul_f32 v[10:11], v[10:11], v[50:51]
	ds_read_b128 v[50:53], v66 offset:39424
	s_waitcnt lgkmcnt(0)
	v_mfma_f32_16x16x32_bf16 v[2:5], v[50:53], v[46:49], v[2:5]
	ds_read_b128 v[50:53], v66 offset:39488
	s_waitcnt lgkmcnt(0)
	v_mfma_f32_16x16x32_bf16 v[2:5], v[50:53], v[42:45], v[2:5]
	ds_read_b128 v[50:53], v67 offset:128
	s_waitcnt lgkmcnt(0)
	s_nop 5
	v_pk_mul_f32 v[4:5], v[4:5], v[52:53]
	v_pk_mul_f32 v[2:3], v[2:3], v[50:51]
	ds_read_b128 v[50:53], v66 offset:41728
	s_waitcnt lgkmcnt(0)
	v_mfma_f32_16x16x32_bf16 v[18:21], v[50:53], v[46:49], v[18:21]
	ds_read_b128 v[50:53], v66 offset:41792
	s_waitcnt lgkmcnt(0)
	v_mfma_f32_16x16x32_bf16 v[18:21], v[50:53], v[42:45], v[18:21]
	ds_read_b128 v[50:53], v67 offset:192
	s_waitcnt lgkmcnt(0)
	s_nop 5
	v_pk_mul_f32 v[20:21], v[20:21], v[52:53]
	v_pk_mul_f32 v[18:19], v[18:19], v[50:51]
	ds_read_b128 v[50:53], v66 offset:44032
	s_waitcnt lgkmcnt(0)
	v_mfma_f32_16x16x32_bf16 v[14:17], v[50:53], v[46:49], v[14:17]
	ds_read_b128 v[50:53], v66 offset:44096
	s_waitcnt lgkmcnt(0)
	v_mfma_f32_16x16x32_bf16 v[14:17], v[50:53], v[42:45], v[14:17]
	ds_read_b128 v[50:53], v67 offset:256
	s_waitcnt lgkmcnt(0)
	s_nop 5
	v_pk_mul_f32 v[16:17], v[16:17], v[52:53]
	v_pk_mul_f32 v[14:15], v[14:15], v[50:51]
	ds_read_b128 v[50:53], v66 offset:46336
	s_waitcnt lgkmcnt(0)
	v_mfma_f32_16x16x32_bf16 v[26:29], v[50:53], v[46:49], v[26:29]
	ds_read_b128 v[50:53], v66 offset:46400
	s_waitcnt lgkmcnt(0)
	v_mfma_f32_16x16x32_bf16 v[26:29], v[50:53], v[42:45], v[26:29]
	ds_read_b128 v[50:53], v67 offset:320
	s_waitcnt lgkmcnt(0)
	s_nop 5
	v_pk_mul_f32 v[28:29], v[28:29], v[52:53]
	v_pk_mul_f32 v[26:27], v[26:27], v[50:51]
	ds_read_b128 v[50:53], v66 offset:48640
	s_waitcnt lgkmcnt(0)
	v_mfma_f32_16x16x32_bf16 v[22:25], v[50:53], v[46:49], v[22:25]
	ds_read_b128 v[50:53], v66 offset:48704
	s_waitcnt lgkmcnt(0)
	v_mfma_f32_16x16x32_bf16 v[22:25], v[50:53], v[42:45], v[22:25]
	ds_read_b128 v[50:53], v67 offset:384
	s_waitcnt lgkmcnt(0)
	s_nop 5
	v_pk_mul_f32 v[24:25], v[24:25], v[52:53]
	v_pk_mul_f32 v[22:23], v[22:23], v[50:51]
	ds_read_b128 v[50:53], v66 offset:50944
	s_waitcnt lgkmcnt(0)
	v_mfma_f32_16x16x32_bf16 v[30:33], v[50:53], v[46:49], v[30:33]
	ds_read_b128 v[50:53], v66 offset:51008
	s_waitcnt lgkmcnt(0)
	v_mfma_f32_16x16x32_bf16 v[30:33], v[50:53], v[42:45], v[30:33]
	ds_read_b128 v[50:53], v67 offset:448
	s_waitcnt lgkmcnt(0)
	s_nop 5
	v_pk_mul_f32 v[30:31], v[30:31], v[50:51]
	v_add_co_u32_e32 v50, vcc, s47, v102
	v_pk_mul_f32 v[32:33], v[32:33], v[52:53]
	s_nop 0
	v_addc_co_u32_e32 v51, vcc, 0, v103, vcc
	global_load_dwordx4 v[66:69], v[50:51], off offset:512
	v_add_co_u32_e32 v50, vcc, s47, v100
	s_nop 1
	v_addc_co_u32_e32 v51, vcc, 0, v101, vcc
	global_load_dwordx4 v[50:53], v[50:51], off offset:512
	s_barrier
; #define LAS __attribute__((address_space(3)))
; DI float bflo(unsigned w) { return __uint_as_float(w << 16); }
; DI float bfhi(unsigned w) { return __uint_as_float(w & 0xffff0000u); }
; DI u32x4 pack8(f32x4 a, f32x4 b) { u32x4 w; w.x = pk2(a[0], a[1]); w.y = pk2(a[2], a[3]); w.z = pk2(b[0], b[1]); w.w = pk2(b[2], b[3]); return w; }
; #define MFMA16(a, b, c) __builtin_amdgcn_mfma_f32_16x16x32_bf16((a), (b), (c), 0, 0, 0)
; template <bool OUT> DI void hgrn_item(LAS unsigned char* lds, bf16_t* proj, float* hst, float* hdv, const float* normw, int item, bool dry) {
;     ...
;                 for (int ks = 0; ks < 2; ++ks) if (2 * ks <= ti) { const bf16x8 aa = *(const LAS bf16x8*)(Ab + (16 * ti + e16) * TP + 32 * ks + 8 * rq); o[ti] = MFMA16(aa, vfr[ks], o[ti]); }
;             LAS float* Ob = (LAS float*)(lds + HOB_OFF);
; #pragma unroll
;             for (int ti = 0; ti < 4; ++ti)
; #pragma unroll
;                 for (int r = 0; r < 4; ++r) Ob[(16 * ti + 4 * rq + r) * OBP + w * 16 + e16] = o[ti][r];
;             __syncthreads();
; #pragma unroll
;             for (int j = 0; j < 2; ++j) { const int cch = tid + 512 * j, tt = cch >> 4, e0 = 8 * (cch & 15);
;                 const f32x4 a0 = *(const LAS f32x4*)(Ob + tt * OBP + e0), a1 = *(const LAS f32x4*)(Ob + tt * OBP + e0 + 4);
;                 float q = (a0[0] * a0[0] + a0[1] * a0[1]) + (a0[2] * a0[2] + a0[3] * a0[3]) + (a1[0] * a1[0] + a1[1] * a1[1]) + (a1[2] * a1[2] + a1[3] * a1[3]);
;                 q += __shfl_xor(q, 1); q += __shfl_xor(q, 2); q += __shfl_xor(q, 4); q += __shfl_xor(q, 8);
;                 const float rs = __builtin_amdgcn_rsqf(q * (1.0f / 128.0f) + 1e-6f);
;                 const f32x4 n0 = *(const f32x4*)(normw + e0), n1 = *(const f32x4*)(normw + e0 + 4); const u32x4 g = gate8[j];
;                 f32x4 y0, y1;
;                 y0[0] = a0[0] * rs * n0[0] * bflo(g.x); y0[1] = a0[1] * rs * n0[1] * bfhi(g.x); y0[2] = a0[2] * rs * n0[2] * bflo(g.y); y0[3] = a0[3] * rs * n0[3] * bfhi(g.y);
;                 y1[0] = a1[0] * rs * n1[0] * bflo(g.z); y1[1] = a1[1] * rs * n1[1] * bfhi(g.z); y1[2] = a1[2] * rs * n1[2] * bflo(g.w); y1[3] = a1[3] * rs * n1[3] * bfhi(g.w);
;                 if (!dry) *(u32x4*)(proj + (row0 + tt) * NPJ + C_HQ + h * 128 + e0) = pack8(y0, y1); }
	ds_read_b128 v[144:147], v116
	s_waitcnt lgkmcnt(0)
	v_mfma_f32_16x16x32_bf16 v[54:57], v[144:147], v[46:49], v[54:57]
	ds_read_b128 v[144:147], v116 offset:2304
	s_waitcnt lgkmcnt(0)
	v_mfma_f32_16x16x32_bf16 v[58:61], v[144:147], v[46:49], v[58:61]
	ds_read_b128 v[144:147], v116 offset:4608
	s_waitcnt lgkmcnt(0)
	v_mfma_f32_16x16x32_bf16 v[62:65], v[144:147], v[46:49], v[62:65]
	ds_read_b128 v[144:147], v116 offset:4672
	s_waitcnt lgkmcnt(0)
	v_mfma_f32_16x16x32_bf16 v[62:65], v[144:147], v[42:45], v[62:65]
	ds_read_b128 v[144:147], v116 offset:6912
	s_waitcnt lgkmcnt(0)
	v_mfma_f32_16x16x32_bf16 v[46:49], v[144:147], v[46:49], v[70:73]
	s_nop 2
	ds_read_b128 v[70:73], v116 offset:6976
	ds_write2_b32 v125, v54, v55 offset1:132
	s_waitcnt lgkmcnt(1)
	v_mfma_f32_16x16x32_bf16 v[42:45], v[70:73], v[42:45], v[46:49]
	s_nop 2
	v_add_u32_e32 v46, 0x400, v125
	ds_write2_b32 v46, v56, v57 offset0:8 offset1:140
	v_add_u32_e32 v46, 0x2000, v125
	ds_write2_b32 v46, v58, v59 offset0:64 offset1:196
	v_add_u32_e32 v46, 0x2400, v125
	ds_write2_b32 v46, v60, v61 offset0:72 offset1:204
	v_add_u32_e32 v46, 0x4200, v125
	ds_write2_b32 v46, v62, v63 offset1:132
	v_add_u32_e32 v46, 0x4600, v125
	ds_write2_b32 v46, v64, v65 offset0:8 offset1:140
	v_add_u32_e32 v46, 0x6200, v125
	ds_write2_b32 v46, v42, v43 offset0:64 offset1:196
	v_add_u32_e32 v42, 0x6600, v125
	ds_write2_b32 v42, v44, v45 offset0:72 offset1:204
	s_waitcnt lgkmcnt(0)
	s_barrier
	ds_read_b128 v[42:45], v117
	ds_read_b128 v[46:49], v117 offset:16
	s_waitcnt vmcnt(1)
	v_lshlrev_b32_e32 v64, 16, v68
	v_and_b32_e32 v65, 0xffff0000, v68
	s_waitcnt lgkmcnt(1)
	v_pk_mul_f32 v[54:55], v[44:45], v[44:45]
	v_pk_mul_f32 v[56:57], v[42:43], v[42:43]
	s_nop 0
	v_pk_mov_b32 v[58:59], v[56:57], v[54:55] op_sel:[1,0]
	v_mov_b32_e32 v57, v55
	v_pk_add_f32 v[54:55], v[58:59], v[56:57]
	s_waitcnt lgkmcnt(0)
	v_pk_mul_f32 v[56:57], v[48:49], v[48:49]
	v_pk_mul_f32 v[58:59], v[46:47], v[46:47]
	v_mov_b32_e32 v60, v56
	v_mov_b32_e32 v61, v58
	v_mov_b32_e32 v58, v57
	v_pk_add_f32 v[56:57], v[60:61], v[58:59]
	v_add_f32_e32 v54, v54, v55
	v_add_f32_e32 v54, v54, v57
	v_add_f32_e32 v54, v56, v54
	s_nop 1
	v_add_f32_dpp v54, v54, v54 quad_perm:[1,0,3,2] row_mask:0xf bank_mask:0xf
	s_nop 1
	v_add_f32_dpp v54, v54, v54 quad_perm:[2,3,0,1] row_mask:0xf bank_mask:0xf
	s_nop 1
	v_add_f32_dpp v62, v54, v54 row_half_mirror row_mask:0xf bank_mask:0xf
	s_nop 1
	v_add_f32_dpp v62, v62, v62 row_mirror row_mask:0xf bank_mask:0xf
	v_fmamk_f32 v62, v62, 0x3c000000, v118
	v_rsq_f32_e32 v62, v62
	s_nop 0
	v_pk_mul_f32 v[46:47], v[46:47], v[62:63] op_sel_hi:[1,0]
	v_pk_mul_f32 v[48:49], v[48:49], v[62:63] op_sel_hi:[1,0]
	v_pk_mul_f32 v[42:43], v[42:43], v[62:63] op_sel_hi:[1,0]
	v_pk_mul_f32 v[44:45], v[44:45], v[62:63] op_sel_hi:[1,0]
	s_waitcnt vmcnt(0)
	v_pk_mul_f32 v[42:43], v[232:233], v[42:43]
	v_pk_mul_f32 v[46:47], v[236:237], v[46:47]
	v_lshlrev_b32_e32 v58, 16, v69
	v_and_b32_e32 v59, 0xffff0000, v69
	v_pk_mul_f32 v[48:49], v[238:239], v[48:49]
	v_lshlrev_b32_e32 v54, 16, v67
	v_pk_mul_f32 v[48:49], v[48:49], v[58:59]
	v_lshlrev_b32_e32 v58, 16, v66
	v_and_b32_e32 v59, 0xffff0000, v66
	v_and_b32_e32 v55, 0xffff0000, v67
	v_pk_mul_f32 v[44:45], v[234:235], v[44:45]
	v_pk_mul_f32 v[46:47], v[46:47], v[64:65]
	v_pk_mul_f32 v[42:43], v[42:43], v[58:59]
	v_pk_mul_f32 v[44:45], v[44:45], v[54:55]
	v_cvt_pk_bf16_f32 v42, v42, v43
	v_cvt_pk_bf16_f32 v43, v44, v45
	v_cvt_pk_bf16_f32 v44, v46, v47
	v_cvt_pk_bf16_f32 v45, v48, v49
	global_store_dwordx4 v[102:103], v[42:45], off offset:1536
	ds_read_b128 v[42:45], v119
	ds_read_b128 v[46:49], v119 offset:16
	v_lshlrev_b32_e32 v64, 16, v52
	v_and_b32_e32 v65, 0xffff0000, v52
	v_lshlrev_b32_e32 v52, 16, v53
	s_waitcnt lgkmcnt(1)
	v_pk_mul_f32 v[54:55], v[44:45], v[44:45]
	v_pk_mul_f32 v[56:57], v[42:43], v[42:43]
	v_and_b32_e32 v53, 0xffff0000, v53
	v_pk_mov_b32 v[58:59], v[56:57], v[54:55] op_sel:[1,0]
	v_mov_b32_e32 v57, v55
	v_pk_add_f32 v[54:55], v[58:59], v[56:57]
	s_waitcnt lgkmcnt(0)
	v_pk_mul_f32 v[56:57], v[48:49], v[48:49]
	v_pk_mul_f32 v[58:59], v[46:47], v[46:47]
	v_mov_b32_e32 v60, v56
	v_mov_b32_e32 v61, v58
	v_mov_b32_e32 v58, v57
	v_pk_add_f32 v[56:57], v[60:61], v[58:59]
	v_add_f32_e32 v54, v54, v55
	v_add_f32_e32 v54, v54, v57
	v_add_f32_e32 v54, v56, v54
	s_nop 1
	v_add_f32_dpp v54, v54, v54 quad_perm:[1,0,3,2] row_mask:0xf bank_mask:0xf
	s_nop 1
	v_add_f32_dpp v54, v54, v54 quad_perm:[2,3,0,1] row_mask:0xf bank_mask:0xf
	s_nop 1
	v_add_f32_dpp v62, v54, v54 row_half_mirror row_mask:0xf bank_mask:0xf
	s_nop 1
	v_add_f32_dpp v62, v62, v62 row_mirror row_mask:0xf bank_mask:0xf
	v_fmamk_f32 v62, v62, 0x3c000000, v118
	v_rsq_f32_e32 v62, v62
	s_nop 0
	v_pk_mul_f32 v[48:49], v[48:49], v[62:63] op_sel_hi:[1,0]
	v_pk_mul_f32 v[46:47], v[46:47], v[62:63] op_sel_hi:[1,0]
	v_pk_mul_f32 v[42:43], v[42:43], v[62:63] op_sel_hi:[1,0]
	v_pk_mul_f32 v[44:45], v[44:45], v[62:63] op_sel_hi:[1,0]
	v_pk_mul_f32 v[42:43], v[232:233], v[42:43]
	v_pk_mul_f32 v[48:49], v[238:239], v[48:49]
	v_pk_mul_f32 v[46:47], v[236:237], v[46:47]
	v_pk_mul_f32 v[48:49], v[48:49], v[52:53]
	v_lshlrev_b32_e32 v52, 16, v50
	v_and_b32_e32 v53, 0xffff0000, v50
	v_lshlrev_b32_e32 v50, 16, v51
	v_and_b32_e32 v51, 0xffff0000, v51
	v_pk_mul_f32 v[44:45], v[234:235], v[44:45]
	v_pk_mul_f32 v[46:47], v[46:47], v[64:65]
	v_pk_mul_f32 v[42:43], v[42:43], v[52:53]
	v_pk_mul_f32 v[44:45], v[44:45], v[50:51]
	v_cvt_pk_bf16_f32 v42, v42, v43
	v_cvt_pk_bf16_f32 v43, v44, v45
	v_cvt_pk_bf16_f32 v44, v46, v47
	v_cvt_pk_bf16_f32 v45, v48, v49
	global_store_dwordx4 v[100:101], v[42:45], off offset:1536
	s_waitcnt vmcnt(1)
	v_lshl_or_b32 v129, v185, 16, v184
	v_lshl_or_b32 v127, v190, 16, v191
	v_lshl_or_b32 v131, v192, 16, v188
	v_lshl_or_b32 v128, v194, 16, v189
	v_lshl_or_b32 v133, v196, 16, v195
	v_lshl_or_b32 v135, v203, 16, v202
	v_lshl_or_b32 v134, v214, 16, v215
	v_lshl_or_b32 v34, v187, 16, v186
	v_lshl_or_b32 v35, v199, 16, v193
	v_lshl_or_b32 v36, v200, 16, v197
	v_lshl_or_b32 v130, v198, 16, v201
	v_lshl_or_b32 v37, v205, 16, v204
	v_lshl_or_b32 v132, v206, 16, v207
	v_lshl_or_b32 v137, v209, 16, v208
	v_lshl_or_b32 v38, v211, 16, v210
	v_lshl_or_b32 v139, v216, 16, v212
	v_lshl_or_b32 v136, v218, 16, v213
	v_lshl_or_b32 v141, v220, 16, v219
	v_lshl_or_b32 v39, v223, 16, v217
	v_lshl_or_b32 v40, v224, 16, v221
	v_lshl_or_b32 v138, v222, 16, v225
	v_lshl_or_b32 v142, v227, 16, v226
	v_lshl_or_b32 v41, v229, 16, v228
	v_lshl_or_b32 v140, v230, 16, v231
	v_mov_b32_e32 v46, v127
	v_mov_b32_e32 v47, v128
	v_mov_b32_e32 v49, v130
	v_mov_b32_e32 v51, v132
	v_mov_b32_e32 v52, v134
	v_mov_b32_e32 v53, v136
	v_mov_b32_e32 v54, v138
	v_mov_b32_e32 v48, v140
	v_mov_b32_e32 v42, v129
	v_mov_b32_e32 v43, v131
	v_mov_b32_e32 v44, v133
	v_mov_b32_e32 v45, v135
	v_mov_b32_e32 v50, v137
	v_mov_b32_e32 v55, v139
	v_mov_b32_e32 v56, v141
	v_mov_b32_e32 v57, v142
	s_cbranch_scc0 .LBB0_1168
